# attention prompt loop: staggered halves, two-tile-deep prefetch, K fragments read up front, permlane max, ILP softmax with PV MFMAs interleaved
# baseline (speedup 1.0000x reference)
; #define LAS __attribute__((address_space(3)))
; __device__ __forceinline__ void load_q(bf16x8 (&qf)[6], const bf16_t* qn, const bf16_t* qr, const float* rp, int hi) {
; #pragma unroll
;     for (int d0 = 0; d0 < 4; ++d0) qf[d0] = *(const bf16x8*)(qn + d0 * 16 + hi * 8);
;     const u32x4 a = *(const u32x4*)(qr + hi * 8), b = *(const u32x4*)(qr + 16 + hi * 8);
;     const f32x4 c0 = *(const f32x4*)(rp + hi * 8), c1 = *(const f32x4*)(rp + hi * 8 + 4), s0 = *(const f32x4*)(rp + 16 + hi * 8), s1 = *(const f32x4*)(rp + 16 + hi * 8 + 4);
;     const float x1[8] = {bflo(a.x), bfhi(a.x), bflo(a.y), bfhi(a.y), bflo(a.z), bfhi(a.z), bflo(a.w), bfhi(a.w)};
;     const float x2[8] = {bflo(b.x), bfhi(b.x), bflo(b.y), bfhi(b.y), bflo(b.z), bfhi(b.z), bflo(b.w), bfhi(b.w)};
;     const float cs[8] = {c0[0], c0[1], c0[2], c0[3], c1[0], c1[1], c1[2], c1[3]}, sn[8] = {s0[0], s0[1], s0[2], s0[3], s1[0], s1[1], s1[2], s1[3]};
;     float o1[8], o2[8];
; #pragma unroll
;     for (int j = 0; j < 8; ++j) { o1[j] = x1[j] * cs[j] - x2[j] * sn[j]; o2[j] = x1[j] * sn[j] + x2[j] * cs[j]; }
;     u32x4 w1 = (u32x4){pk2(o1[0], o1[1]), pk2(o1[2], o1[3]), pk2(o1[4], o1[5]), pk2(o1[6], o1[7])}, w2 = (u32x4){pk2(o2[0], o2[1]), pk2(o2[2], o2[3]), pk2(o2[4], o2[5]), pk2(o2[6], o2[7])};
;     qf[4] = __builtin_bit_cast(bf16x8, w1); qf[5] = __builtin_bit_cast(bf16x8, w2);
; }
; __device__ __forceinline__ void prompt_unit(LAS unsigned char* lds, const Ptrs& P, int qloc0, int qglob0, int kloc0, int kglob0, int h, int qb) {
;     int tid_ = threadIdx.x; asm volatile("" : "+v"(tid_));
;     const int tid = tid_, lane = tid & 63, r32 = lane & 31, hi = lane >> 5; const int wid = __builtin_amdgcn_readfirstlane(tid >> 6);
;     const int NTL = 4 * qb + 4, cq = 4 * qb + (wid >> 1);
;     bf16x8 qf[6];
;     { const int ql = qloc0 + 32 * wid + r32, pos = qb * 256 + 32 * wid + r32;
;       load_q(qf, P.Qn + (size_t)ql * 1024 + h * 64, P.Qr + (size_t)ql * 512 + h * 32, P.rope + pos * 32, hi); }
;     const bf16_t* kn_src = P.Kn + (size_t)(kloc0 + (tid >> 3)) * 1024 + h * 64 + (tid & 7) * 8;
;     const bf16_t* vt_src = P.Vt + (size_t)(h * 64 + (tid >> 3)) * VT_LD + kloc0 + (tid & 7) * 8;
;     const bf16_t* kr_src = P.KR + (size_t)(kglob0 + ((tid & 255) >> 2)) * 32 + (tid & 3) * 8;
;     const int k_w = (tid >> 3) * KP + (tid & 7) * 16, r_w = ((tid & 255) >> 2) * KP + 128 + (tid & 3) * 16;
.LBB0_1143:
	s_waitcnt vmcnt(0)
	v_mov_b32_e32 v16, v167
	s_and_b64 s[38:39], s[66:67], exec
	s_cselect_b32 s68, s3, s25
	v_readfirstlane_b32 s69, v16
	s_ashr_i32 s39, s69, 1
	s_lshl_b32 s27, s68, 8
	s_and_b32 s64, s39, 0xffffffe0
	v_mov_b32_e32 v0, s39
	s_movk_i32 s39, 0xffe0
	s_or_b32 s38, s27, s8
	v_bfi_b32 v143, s39, v0, v16
	v_add_u32_e32 v0, s38, v143
	v_and_b32_e32 v17, 31, v16
	s_add_i32 s64, s64, s27
	v_ashrrev_i32_e32 v1, 31, v0
	v_bfe_u32 v142, v16, 5, 1
	v_or_b32_e32 v4, s64, v17
	v_lshlrev_b64 v[2:3], 11, v[0:1]
	v_lshlrev_b64 v[0:1], 10, v[0:1]
	v_lshl_add_u64 v[2:3], s[16:17], 0, v[2:3]
	v_lshl_add_u64 v[0:1], s[22:23], 0, v[0:1]
	v_lshlrev_b32_e32 v4, 5, v4
	v_lshlrev_b32_e32 v64, 4, v142
	v_ashrrev_i32_e32 v5, 31, v4
	v_lshl_add_u64 v[2:3], v[2:3], 0, v[64:65]
	v_lshl_add_u64 v[0:1], v[0:1], 0, v[64:65]
	v_lshl_add_u64 v[4:5], v[4:5], 2, s[14:15]
	global_load_dwordx4 v[78:81], v[2:3], off
	global_load_dwordx4 v[74:77], v[2:3], off offset:32
	global_load_dwordx4 v[70:73], v[2:3], off offset:64
	s_waitcnt lgkmcnt(0)
	global_load_dwordx4 v[66:69], v[2:3], off offset:96
	global_load_dwordx4 v[8:11], v[0:1], off
	global_load_dwordx4 v[12:15], v[0:1], off offset:32
	v_lshlrev_b32_e32 v0, 5, v142
	v_mov_b32_e32 v1, v65
	v_lshl_add_u64 v[22:23], v[4:5], 0, v[0:1]
	global_load_dwordx4 v[0:3], v[22:23], off offset:16
	global_load_dwordx4 v[18:21], v[22:23], off
	global_load_dwordx4 v[4:7], v[22:23], off offset:80
	s_nop 0
	global_load_dwordx4 v[22:25], v[22:23], off offset:64
	v_mov_b32_e32 v90, v65
	v_mov_b32_e32 v91, v65
	v_mov_b32_e32 v92, v65
	v_mov_b32_e32 v93, v65
	s_waitcnt vmcnt(5)
	v_lshlrev_b32_e32 v27, 16, v8
	s_waitcnt vmcnt(4)
	v_lshlrev_b32_e32 v26, 16, v12
	s_waitcnt vmcnt(2)
	v_mov_b32_e32 v29, v18
	s_waitcnt vmcnt(0)
	v_mov_b32_e32 v28, v22
	v_pk_mul_f32 v[28:29], v[28:29], v[26:27]
	s_nop 0
	v_sub_f32_e32 v30, v29, v28
	v_mov_b32_e32 v28, v18
	v_mov_b32_e32 v29, v22
	v_pk_mul_f32 v[26:27], v[28:29], v[26:27]
	v_mov_b32_e32 v18, v23
	v_add_f32_e32 v31, v26, v27
	v_and_b32_e32 v27, 0xffff0000, v8
	v_and_b32_e32 v26, 0xffff0000, v12
	v_mov_b32_e32 v22, v19
	v_pk_mul_f32 v[28:29], v[18:19], v[26:27]
	v_pk_mul_f32 v[18:19], v[22:23], v[26:27]
	v_mov_b32_e32 v22, v24
	v_add_f32_e32 v26, v18, v19
	v_lshlrev_b32_e32 v19, 16, v9
	v_lshlrev_b32_e32 v18, 16, v13
	v_mov_b32_e32 v23, v20
	v_pk_mul_f32 v[22:23], v[22:23], v[18:19]
	v_and_b32_e32 v9, 0xffff0000, v9
	v_sub_f32_e32 v27, v23, v22
	v_mov_b32_e32 v22, v20
	v_mov_b32_e32 v23, v24
	v_and_b32_e32 v8, 0xffff0000, v13
	v_mov_b32_e32 v20, v25
	v_mov_b32_e32 v24, v21
	v_pk_mul_f32 v[18:19], v[22:23], v[18:19]
	v_pk_mul_f32 v[12:13], v[20:21], v[8:9]
	v_pk_mul_f32 v[8:9], v[24:25], v[8:9]
	v_add_f32_e32 v18, v18, v19
	v_sub_f32_e32 v19, v13, v12
	v_add_f32_e32 v20, v8, v9
	v_lshlrev_b32_e32 v9, 16, v10
	v_lshlrev_b32_e32 v8, 16, v14
	v_mov_b32_e32 v12, v4
	v_mov_b32_e32 v13, v0
	v_pk_mul_f32 v[12:13], v[12:13], v[8:9]
	v_sub_f32_e32 v28, v29, v28
	v_sub_f32_e32 v21, v13, v12
	v_mov_b32_e32 v12, v0
	v_mov_b32_e32 v13, v4
	v_pk_mul_f32 v[8:9], v[12:13], v[8:9]
	v_mov_b32_e32 v0, v5
	v_add_f32_e32 v22, v8, v9
	v_and_b32_e32 v9, 0xffff0000, v10
	v_and_b32_e32 v8, 0xffff0000, v14
	v_mov_b32_e32 v4, v1
	v_pk_mul_f32 v[12:13], v[0:1], v[8:9]
	v_pk_mul_f32 v[0:1], v[4:5], v[8:9]
	v_mov_b32_e32 v4, v6
	v_add_f32_e32 v8, v0, v1
	v_lshlrev_b32_e32 v1, 16, v11
	v_lshlrev_b32_e32 v0, 16, v15
	v_mov_b32_e32 v5, v2
	v_pk_mul_f32 v[4:5], v[4:5], v[0:1]
	v_sub_f32_e32 v10, v13, v12
	v_sub_f32_e32 v9, v5, v4
	v_mov_b32_e32 v4, v2
	v_mov_b32_e32 v5, v6
	v_pk_mul_f32 v[0:1], v[4:5], v[0:1]
	v_mov_b32_e32 v2, v7
	v_add_f32_e32 v12, v0, v1
	v_and_b32_e32 v1, 0xffff0000, v11
	v_and_b32_e32 v0, 0xffff0000, v15
	v_mov_b32_e32 v6, v3
	v_pk_mul_f32 v[4:5], v[2:3], v[0:1]
	v_pk_mul_f32 v[0:1], v[6:7], v[0:1]
	v_sub_f32_e32 v2, v5, v4
	v_add_f32_e32 v0, v0, v1
	v_cvt_pk_bf16_f32 v86, v30, v28
	v_cvt_pk_bf16_f32 v87, v27, v19
	v_cvt_pk_bf16_f32 v88, v21, v10
	v_cvt_pk_bf16_f32 v89, v9, v2
	v_cvt_pk_bf16_f32 v82, v31, v26
	v_cvt_pk_bf16_f32 v83, v18, v20
	v_cvt_pk_bf16_f32 v84, v22, v8
	v_cvt_pk_bf16_f32 v85, v12, v0
	v_ashrrev_i32_e32 v12, 3, v16
	v_add_u32_e32 v0, s8, v12
	v_ashrrev_i32_e32 v1, 31, v0
	v_and_b32_e32 v2, 7, v16
	v_lshlrev_b64 v[0:1], 11, v[0:1]
	v_lshlrev_b32_e32 v8, 4, v2
	v_add_u32_e32 v4, s26, v12
	v_mov_b64_e32 v[2:3], s[30:31]
	v_lshl_add_u64 v[0:1], s[28:29], 0, v[0:1]
	v_mov_b32_e32 v9, v65
	v_mad_i64_i32 v[2:3], s[38:39], v4, s77, v[2:3]
	v_lshl_add_u64 v[0:1], v[0:1], 0, v[8:9]
	v_lshl_add_u64 v[2:3], v[2:3], 0, v[8:9]
	v_add_co_u32_e32 v98, vcc, 0x20000, v0
	s_nop 1
	v_addc_co_u32_e32 v99, vcc, 0, v1, vcc
	v_add_co_u32_e32 v180, vcc, 0x40000, v0
	s_nop 1
	v_addc_co_u32_e32 v181, vcc, 0, v1, vcc
	v_lshl_add_u64 v[94:95], v[2:3], 0, s[44:45]
	v_lshl_add_u64 v[176:177], v[94:95], 0, s[44:45]
	global_load_dwordx4 v[4:7], v[0:1], off
	s_nop 0
	global_load_dwordx4 v[0:3], v[2:3], off
	s_movk_i32 s38, 0xff
	v_and_b32_e32 v9, 3, v16
	v_cmp_lt_i32_e32 vcc, s38, v16
	s_movk_i32 s38, 0x100
	v_bfe_u32 v13, v16, 2, 6
	v_cmp_gt_i32_e64 s[38:39], s38, v16
	v_lshlrev_b32_e32 v10, 4, v9
	s_and_saveexec_b64 s[64:65], s[38:39]
	s_cbranch_execz .LBB0_1145
	v_or_b32_e32 v14, s24, v13
	v_ashrrev_i32_e32 v15, 31, v14
	v_lshlrev_b64 v[14:15], 6, v[14:15]
	v_lshl_add_u64 v[14:15], s[12:13], 0, v[14:15]
	v_mov_b32_e32 v11, v65
	v_lshl_add_u64 v[14:15], v[14:15], 0, v[10:11]
	global_load_dwordx4 v[102:105], v[14:15], off
	v_lshl_add_u64 v[14:15], v[14:15], 0, s[34:35]
	global_load_dwordx4 v[90:93], v[14:15], off
	v_lshl_add_u64 v[14:15], v[14:15], 0, s[34:35]
	global_load_dwordx4 v[172:175], v[14:15], off
; #define LAS __attribute__((address_space(3)))
; __device__ __forceinline__ void prompt_unit(LAS unsigned char* lds, const Ptrs& P, int qloc0, int qglob0, int kloc0, int kglob0, int h, int qb) {
;     ...
;     kreg = *(const u32x4*)kn_src; vreg = *(const u32x4*)vt_src; if (tid < 256) rreg = *(const u32x4*)kr_src;
;     *(LAS u32x4*)(lds + k_w) = kreg; if (tid < 256) *(LAS u32x4*)(lds + r_w) = rreg;
;     *(LAS u32x2*)(lds + v_w) = (u32x2){vreg.x, vreg.y}; *(LAS u32x2*)(lds + v_w + 16) = (u32x2){vreg.z, vreg.w};
;     __syncthreads();
;     float m = -1e30f, l = 0.f; f32x16 o[2];
; #pragma unroll
;     for (int r = 0; r < 16; ++r) { o[0][r] = 0.f; o[1][r] = 0.f; }
;     for (int j = 0; j < NTL; ++j) {
;         const bool more = j + 1 < NTL;
;         if (more) { kreg = *(const u32x4*)(kn_src + (size_t)(j + 1) * 64 * 1024); vreg = *(const u32x4*)(vt_src + (j + 1) * 64); if (tid < 256) rreg = *(const u32x4*)(kr_src + (size_t)(j + 1) * 64 * 32); }
.LBB0_1145:
	s_or_b64 exec, exec, s[64:65]
	global_load_dwordx4 v[98:101], v[98:99], off
	global_load_dwordx4 v[94:97], v[94:95], off
	global_load_dwordx4 v[180:183], v[180:181], off
	global_load_dwordx4 v[176:179], v[176:177], off
	s_movk_i32 s64, 0xd0
	v_mad_u64_u32 v[134:135], s[64:65], v12, s64, v[8:9]
	v_mul_u32_u24_e32 v11, 0xd0, v13
	v_add_u32_e32 v14, 0, v134
	v_add_u32_e32 v146, v10, v11
	s_waitcnt vmcnt(5)
	ds_write_b128 v14, v[4:7]
	s_and_saveexec_b64 s[64:65], vcc
	s_xor_b64 s[64:65], exec, s[64:65]
	v_add_u32_e32 v146, v10, v11
	s_andn2_saveexec_b64 s[64:65], s[64:65]
	s_cbranch_execz .LBB0_1149
	v_add_u32_e32 v4, 0, v146
	s_waitcnt vmcnt(5)
	ds_write_b128 v4, v[102:105] offset:128
.LBB0_1149:
	s_or_b64 exec, exec, s[64:65]
	s_xor_b64 s[64:65], s[66:67], -1
	s_movk_i32 s67, 0x90
	v_mul_lo_u32 v4, v12, s67
	v_lshlrev_b32_e32 v6, 3, v16
	v_and_b32_e32 v5, 0x60, v8
	v_and_or_b32 v4, v6, 8, v4
	v_add_u32_e32 v148, v4, v5
	v_add_u32_e32 v4, 0, v148
	v_add_u32_e32 v4, 0x3000, v4
	s_lshl_b32 s66, s68, 2
	s_ashr_i32 s68, s69, 7
	s_waitcnt vmcnt(4)
	ds_write2_b64 v4, v[0:1], v[2:3] offset0:128 offset1:130
	v_lshlrev_b32_e32 v2, 4, v16
	s_add_i32 s69, s68, s66
	s_or_b32 s70, s66, 3
	v_mad_i64_i32 v[0:1], s[66:67], v12, s77, 0
	v_and_b32_e32 v2, 0x70, v2
	v_or_b32_e32 v0, v0, v2
	v_lshl_add_u64 v[136:137], s[40:41], 0, v[0:1]
	v_add_u32_e32 v0, s9, v13
	v_ashrrev_i32_e32 v1, 31, v0
	v_lshlrev_b64 v[0:1], 6, v[0:1]
	v_lshl_or_b32 v0, v9, 4, v0
	v_lshl_add_u64 v[138:139], s[96:97], 0, v[0:1]
	v_add_u32_e32 v0, s2, v12
	v_ashrrev_i32_e32 v1, 31, v0
	v_lshlrev_b64 v[0:1], 11, v[0:1]
	v_or_b32_e32 v0, v0, v2
	v_mul_u32_u24_e32 v147, 0xd0, v17
	v_mul_u32_u24_e32 v145, 0x90, v17
	v_add_u32_e32 v149, 0, v64
	v_lshl_add_u64 v[140:141], s[42:43], 0, v[0:1]
	s_mov_b64 s[66:67], 0x100
	v_lshl_add_u64 v[136:137], v[136:137], 0, s[66:67]
	s_mov_b64 s[66:67], 0x2000
	v_lshl_add_u64 v[138:139], v[138:139], 0, s[66:67]
	s_mov_b64 s[66:67], 0x40000
	s_mov_b32 s71, 0
	v_lshl_add_u64 v[140:141], v[140:141], 0, s[66:67]
	v_mov_b32_e32 v16, v65
	v_mov_b32_e32 v17, v65
	v_mov_b32_e32 v18, v65
	v_mov_b32_e32 v19, v65
	v_mov_b32_e32 v20, v65
	v_mov_b32_e32 v21, v65
	v_mov_b32_e32 v22, v65
	v_mov_b32_e32 v23, v65
	v_mov_b32_e32 v24, v65
	v_mov_b32_e32 v25, v65
	v_mov_b32_e32 v26, v65
	v_mov_b32_e32 v27, v65
	v_mov_b32_e32 v28, v65
	v_mov_b32_e32 v29, v65
	v_mov_b32_e32 v30, v65
	v_mov_b32_e32 v31, v65
	v_mov_b32_e32 v0, v65
	v_mov_b32_e32 v1, v65
	v_mov_b32_e32 v2, v65
	v_mov_b32_e32 v3, v65
	v_mov_b32_e32 v4, v65
	v_mov_b32_e32 v5, v65
	v_mov_b32_e32 v6, v65
	v_mov_b32_e32 v7, v65
	v_mov_b32_e32 v8, v65
	v_mov_b32_e32 v9, v65
	v_mov_b32_e32 v10, v65
	v_mov_b32_e32 v11, v65
	v_mov_b32_e32 v12, v65
	v_mov_b32_e32 v13, v65
	v_mov_b32_e32 v14, v65
	v_mov_b32_e32 v15, v65
	v_mov_b32_e32 v144, 0xf149f2ca
	v_mov_b32_e32 v135, 0
	s_waitcnt lgkmcnt(0)
	s_barrier
	s_mov_b32 s72, 0
	s_cmp_lt_u32 s68, 2
	s_cbranch_scc1 .LBB0_1151
	s_barrier
.LBB0_1151:
	s_add_i32 s66, s72, 0x5800
	s_cmp_ge_u32 s66, 0x10800
	s_cselect_b32 s66, 0, s66
	v_add_u32_e32 v32, s66, v134
	v_add_u32_e32 v33, s66, v148
	v_add_u32_e32 v34, s66, v146
	v_add_u32_e32 v33, 0x3000, v33
	s_add_i32 s66, s71, 2
	s_cmp_gt_u32 s66, s70
	s_cbranch_scc1 .Latt_wait_all
	s_waitcnt vmcnt(2)
	s_branch .Latt_wait_done

; #define LAS __attribute__((address_space(3)))
; __device__ __forceinline__ float fmax3(float a, float b, float c) { return fmaxf(fmaxf(a, b), c); }
; __device__ __forceinline__ void tile_core(const bf16x8 (&kf)[2][6], const bf16x8 (&vf)[2][4], const bf16x8 (&qf)[6], float& m, float& l, f32x16 (&o)[2], int nvalid, int hi) {
;     ...
;     for (int d0 = 0; d0 < 6; ++d0) { p0 = __builtin_amdgcn_mfma_f32_32x32x16_bf16(kf[0][d0], qf[d0], p0, 0, 0, 0); p1 = __builtin_amdgcn_mfma_f32_32x32x16_bf16(kf[1][d0], qf[d0], p1, 0, 0, 0); }
;     if (nvalid < 64) {
; #pragma unroll
;         for (int r = 0; r < 16; ++r) { const int kv = (r & 3) + 8 * (r >> 2) + 4 * hi; if (kv >= nvalid) p0[r] = -1e30f; if (kv + 32 >= nvalid) p1[r] = -1e30f; }
;     }
;     float rm = fmax3(p0[0], p0[1], p1[0]);
; #pragma unroll
;     for (int r = 1; r < 16; ++r) rm = fmax3(rm, p0[r], p1[r]);
;     rm = fmaxf(rm, __shfl_xor(rm, 32));
;     if (__any(rm > m + 8.0f)) { const float mn = fmaxf(m, rm), f = __builtin_amdgcn_exp2f(m - mn); l *= f; m = mn;
; __device__ __forceinline__ void prompt_unit(LAS unsigned char* lds, const Ptrs& P, int qloc0, int qglob0, int kloc0, int kglob0, int h, int qb) {
;     ...
;     for (int j = 0; j < NTL; ++j) {
;         const bool more = j + 1 < NTL;
;         if (more) { kreg = *(const u32x4*)(kn_src + (size_t)(j + 1) * 64 * 1024); vreg = *(const u32x4*)(vt_src + (j + 1) * 64); if (tid < 256) rreg = *(const u32x4*)(kr_src + (size_t)(j + 1) * 64 * 32); }
;         if (j <= cq) {
;             const LAS unsigned char* buf = lds + (j & 1) * BUFB;
;             bf16x8 kf[2][6], vf[2][4];
; #pragma unroll
;             for (int kb = 0; kb < 2; ++kb)
; #pragma unroll
;                 for (int d0 = 0; d0 < 6; ++d0) kf[kb][d0] = *(const LAS bf16x8*)(buf + (kb * 32 + r32) * KP + d0 * 32 + hi * 16);
; #pragma unroll
;             for (int db = 0; db < 2; ++db)
; #pragma unroll
;                 for (int s4 = 0; s4 < 4; ++s4) vf[db][s4] = *(const LAS bf16x8*)(buf + KB + (db * 32 + r32) * VP + s4 * 32 + hi * 16);
.Latt_wait_done:
	s_add_i32 s66, s71, 3
	s_bitcmp1_b32 s71, 0
	s_cbranch_scc1 .Latt_top_odd
	ds_write_b128 v32, v[98:101]
	ds_write2_b64 v33, v[94:95], v[96:97] offset0:128 offset1:130
	s_and_saveexec_b64 vcc, s[38:39]
	s_cbranch_execz .Latt_kr_w_done_e
	ds_write_b128 v34, v[90:93] offset:128
.Latt_kr_w_done_e:
	s_or_b64 exec, exec, vcc
	s_cmp_gt_u32 s66, s70
	s_cbranch_scc1 .LBB0_1153
	global_load_dwordx4 v[98:101], v[140:141], off
	global_load_dwordx4 v[94:97], v[136:137], off
	s_and_saveexec_b64 vcc, s[38:39]
	s_cbranch_execz .Latt_kr_l_done_e
	global_load_dwordx4 v[90:93], v[138:139], off
.Latt_kr_l_done_e:
	s_or_b64 exec, exec, vcc
	s_branch .Latt_adv_ptr
.Latt_top_odd:
	ds_write_b128 v32, v[180:183]
	ds_write2_b64 v33, v[176:177], v[178:179] offset0:128 offset1:130
	s_and_saveexec_b64 vcc, s[38:39]
	s_cbranch_execz .Latt_kr_w_done_o
	ds_write_b128 v34, v[172:175] offset:128
.Latt_kr_w_done_o:
	s_or_b64 exec, exec, vcc
	s_cmp_gt_u32 s66, s70
	s_cbranch_scc1 .LBB0_1153
	global_load_dwordx4 v[180:183], v[140:141], off
	global_load_dwordx4 v[176:179], v[136:137], off
	s_and_saveexec_b64 vcc, s[38:39]
	s_cbranch_execz .Latt_kr_l_done_o
	global_load_dwordx4 v[172:175], v[138:139], off
.Latt_kr_l_done_o:
	s_or_b64 exec, exec, vcc
.Latt_adv_ptr:
	s_mov_b64 s[66:67], 0x20000
	v_lshl_add_u64 v[136:137], v[136:137], 0, s[44:45]
	v_lshl_add_u64 v[138:139], v[138:139], 0, s[34:35]
	v_lshl_add_u64 v[140:141], v[140:141], 0, s[66:67]
.LBB0_1153:
	s_cmp_gt_i32 s71, s69
	s_cbranch_scc1 .Latt_skip_tile
	v_add_u32_e32 v231, s72, v149
	v_add_u32_e32 v229, v231, v147
	v_add_u32_e32 v230, v231, v145
	ds_read_b128 v[184:187], v229
	ds_read_b128 v[208:211], v229 offset:6656
	ds_read_b128 v[188:191], v229 offset:32
	ds_read_b128 v[102:105], v229 offset:6688
	ds_read_b128 v[192:195], v229 offset:64
	ds_read_b128 v[106:109], v229 offset:6720
	ds_read_b128 v[196:199], v229 offset:96
	ds_read_b128 v[110:113], v229 offset:6752
	ds_read_b128 v[200:203], v229 offset:128
	ds_read_b128 v[114:117], v229 offset:6784
	ds_read_b128 v[204:207], v229 offset:160
	ds_read_b128 v[118:121], v229 offset:6816
	ds_read_b128 v[130:133], v230 offset:13312
	ds_read_b128 v[126:129], v230 offset:13344
	ds_read_b128 v[122:125], v230 offset:13376
	s_waitcnt lgkmcnt(14)
	v_mfma_f32_32x32x16_bf16 v[48:63], v[184:187], v[78:81], 0
	s_waitcnt lgkmcnt(13)
	v_mfma_f32_32x32x16_bf16 v[32:47], v[208:211], v[78:81], 0
	s_waitcnt lgkmcnt(12)
	v_mfma_f32_32x32x16_bf16 v[48:63], v[188:191], v[74:77], v[48:63]
	s_waitcnt lgkmcnt(11)
	v_mfma_f32_32x32x16_bf16 v[32:47], v[102:105], v[74:77], v[32:47]
	s_waitcnt lgkmcnt(10)
	v_mfma_f32_32x32x16_bf16 v[48:63], v[192:195], v[70:73], v[48:63]
	s_waitcnt lgkmcnt(9)
	v_mfma_f32_32x32x16_bf16 v[32:47], v[106:109], v[70:73], v[32:47]
	s_waitcnt lgkmcnt(8)
	v_mfma_f32_32x32x16_bf16 v[48:63], v[196:199], v[66:69], v[48:63]
	s_waitcnt lgkmcnt(7)
	v_mfma_f32_32x32x16_bf16 v[32:47], v[110:113], v[66:69], v[32:47]
	s_waitcnt lgkmcnt(6)
	v_mfma_f32_32x32x16_bf16 v[48:63], v[200:203], v[86:89], v[48:63]
	s_waitcnt lgkmcnt(5)
	v_mfma_f32_32x32x16_bf16 v[32:47], v[114:117], v[86:89], v[32:47]
	s_waitcnt lgkmcnt(4)
	v_mfma_f32_32x32x16_bf16 v[48:63], v[204:207], v[82:85], v[48:63]
	s_waitcnt lgkmcnt(3)
	v_mfma_f32_32x32x16_bf16 v[32:47], v[118:121], v[82:85], v[32:47]
	ds_read_b128 v[114:117], v230 offset:13408
	ds_read_b128 v[118:121], v230 offset:17920
	ds_read_b128 v[110:113], v230 offset:17952
	ds_read_b128 v[106:109], v230 offset:17984
	ds_read_b128 v[102:105], v230 offset:18016
	s_nop 6
	v_max3_f32 v150, v48, v49, v50
	v_max3_f32 v151, v32, v33, v34
	v_max3_f32 v152, v51, v52, v53
	v_max3_f32 v153, v35, v36, v37
	v_max3_f32 v150, v150, v54, v55
	v_max3_f32 v151, v151, v38, v39
	v_max3_f32 v152, v152, v56, v57
	v_max3_f32 v153, v153, v40, v41
	v_max3_f32 v150, v150, v58, v59
	v_max3_f32 v151, v151, v42, v43
	v_max3_f32 v152, v152, v60, v61
	v_max3_f32 v153, v153, v44, v45
	v_max3_f32 v150, v150, v62, v63
	v_max3_f32 v151, v151, v46, v47
	v_max3_f32 v150, v150, v151, v152
	v_max_f32_e32 v150, v150, v153
	v_mov_b32_e32 v151, v150
	s_nop 1
	v_permlane32_swap_b32_e32 v151, v150
	v_max_f32_e32 v150, v150, v151
	v_add_f32_e32 v151, 0x41000000, v144
	v_cmp_gt_f32_e32 vcc, v150, v151
	s_cbranch_vccz .LBB0_1156
	v_max_f32_e32 v150, v150, v150
	v_max_f32_e32 v151, v144, v144
	v_max_f32_e32 v150, v151, v150
	v_sub_f32_e32 v144, v144, v150
	v_exp_f32_e32 v144, v144
	s_nop 0
	v_mul_f32_e32 v135, v135, v144
	v_pk_mul_f32 v[14:15], v[14:15], v[144:145] op_sel_hi:[1,0]
	v_pk_mul_f32 v[12:13], v[12:13], v[144:145] op_sel_hi:[1,0]
	v_pk_mul_f32 v[10:11], v[10:11], v[144:145] op_sel_hi:[1,0]
	v_pk_mul_f32 v[8:9], v[8:9], v[144:145] op_sel_hi:[1,0]
	v_pk_mul_f32 v[6:7], v[6:7], v[144:145] op_sel_hi:[1,0]
	v_pk_mul_f32 v[4:5], v[4:5], v[144:145] op_sel_hi:[1,0]
	v_pk_mul_f32 v[2:3], v[2:3], v[144:145] op_sel_hi:[1,0]
	v_pk_mul_f32 v[0:1], v[0:1], v[144:145] op_sel_hi:[1,0]
	v_pk_mul_f32 v[30:31], v[30:31], v[144:145] op_sel_hi:[1,0]
	v_pk_mul_f32 v[28:29], v[28:29], v[144:145] op_sel_hi:[1,0]
	v_pk_mul_f32 v[26:27], v[26:27], v[144:145] op_sel_hi:[1,0]
	v_pk_mul_f32 v[24:25], v[24:25], v[144:145] op_sel_hi:[1,0]
	v_pk_mul_f32 v[22:23], v[22:23], v[144:145] op_sel_hi:[1,0]
	v_pk_mul_f32 v[20:21], v[20:21], v[144:145] op_sel_hi:[1,0]
	v_pk_mul_f32 v[18:19], v[18:19], v[144:145] op_sel_hi:[1,0]
	v_pk_mul_f32 v[16:17], v[16:17], v[144:145] op_sel_hi:[1,0]
	v_mov_b32_e32 v144, v150
; __device__ __forceinline__ unsigned pk2(float lo, float hi) { return pg8::cvt_pk_bf16(lo, hi); }
; __device__ __forceinline__ void tile_core(const bf16x8 (&kf)[2][6], const bf16x8 (&vf)[2][4], const bf16x8 (&qf)[6], float& m, float& l, f32x16 (&o)[2], int nvalid, int hi) {
;     ...
;     if (__any(rm > m + 8.0f)) { const float mn = fmaxf(m, rm), f = __builtin_amdgcn_exp2f(m - mn); l *= f; m = mn;
; #pragma unroll
;         for (int r = 0; r < 16; ++r) { o[0][r] *= f; o[1][r] *= f; } }
;     float s = 0.f;
; #pragma unroll
;     for (int r = 0; r < 16; ++r) { p0[r] = __builtin_amdgcn_exp2f(p0[r] - m); p1[r] = __builtin_amdgcn_exp2f(p1[r] - m); s += p0[r] + p1[r]; }
;     l += s;
;     bf16x8 pa[4];
;     { u32x4 w;
;       w = (u32x4){pk2(p0[0], p0[1]), pk2(p0[2], p0[3]), pk2(p0[4], p0[5]), pk2(p0[6], p0[7])}; pa[0] = __builtin_bit_cast(bf16x8, w);
;       w = (u32x4){pk2(p0[8], p0[9]), pk2(p0[10], p0[11]), pk2(p0[12], p0[13]), pk2(p0[14], p0[15])}; pa[1] = __builtin_bit_cast(bf16x8, w);
;       w = (u32x4){pk2(p1[0], p1[1]), pk2(p1[2], p1[3]), pk2(p1[4], p1[5]), pk2(p1[6], p1[7])}; pa[2] = __builtin_bit_cast(bf16x8, w);
;       w = (u32x4){pk2(p1[8], p1[9]), pk2(p1[10], p1[11]), pk2(p1[12], p1[13]), pk2(p1[14], p1[15])}; pa[3] = __builtin_bit_cast(bf16x8, w); }
; #pragma unroll
;     for (int db = 0; db < 2; ++db)
; #pragma unroll
;         for (int s4 = 0; s4 < 4; ++s4) o[db] = __builtin_amdgcn_mfma_f32_32x32x16_bf16(vf[db][s4], pa[s4], o[db], 0, 0, 0);
.LBB0_1156:
	s_waitcnt lgkmcnt(4)
	s_barrier
	v_sub_f32_e32 v48, v48, v144
	v_sub_f32_e32 v49, v49, v144
	v_sub_f32_e32 v50, v50, v144
	v_sub_f32_e32 v51, v51, v144
	v_sub_f32_e32 v52, v52, v144
	v_sub_f32_e32 v53, v53, v144
	v_sub_f32_e32 v54, v54, v144
	v_sub_f32_e32 v55, v55, v144
	v_sub_f32_e32 v56, v56, v144
	v_sub_f32_e32 v57, v57, v144
	v_sub_f32_e32 v58, v58, v144
	v_sub_f32_e32 v59, v59, v144
	v_sub_f32_e32 v60, v60, v144
	v_sub_f32_e32 v61, v61, v144
	v_sub_f32_e32 v62, v62, v144
	v_sub_f32_e32 v63, v63, v144
	v_exp_f32_e32 v48, v48
	v_exp_f32_e32 v49, v49
	v_exp_f32_e32 v50, v50
	v_exp_f32_e32 v51, v51
	v_exp_f32_e32 v52, v52
	v_exp_f32_e32 v53, v53
	v_exp_f32_e32 v54, v54
	v_exp_f32_e32 v55, v55
	v_exp_f32_e32 v56, v56
	v_exp_f32_e32 v57, v57
	v_exp_f32_e32 v58, v58
	v_exp_f32_e32 v59, v59
	v_exp_f32_e32 v60, v60
	v_exp_f32_e32 v61, v61
	v_exp_f32_e32 v62, v62
	v_exp_f32_e32 v63, v63
	v_sub_f32_e32 v32, v32, v144
	v_sub_f32_e32 v33, v33, v144
	v_sub_f32_e32 v34, v34, v144
	v_sub_f32_e32 v35, v35, v144
	v_sub_f32_e32 v36, v36, v144
	v_sub_f32_e32 v37, v37, v144
	v_sub_f32_e32 v38, v38, v144
	v_sub_f32_e32 v39, v39, v144
	v_cvt_pk_bf16_f32 v184, v48, v49
	v_cvt_pk_bf16_f32 v185, v50, v51
	v_cvt_pk_bf16_f32 v186, v52, v53
	v_cvt_pk_bf16_f32 v187, v54, v55
	v_cvt_pk_bf16_f32 v188, v56, v57
	v_cvt_pk_bf16_f32 v189, v58, v59
	v_cvt_pk_bf16_f32 v190, v60, v61
	v_cvt_pk_bf16_f32 v191, v62, v63
	v_sub_f32_e32 v40, v40, v144
	v_sub_f32_e32 v41, v41, v144
	v_sub_f32_e32 v42, v42, v144
	v_sub_f32_e32 v43, v43, v144
	v_sub_f32_e32 v44, v44, v144
	v_sub_f32_e32 v45, v45, v144
	v_sub_f32_e32 v46, v46, v144
	v_sub_f32_e32 v47, v47, v144
	s_waitcnt lgkmcnt(0)
	v_mfma_f32_32x32x16_bf16 v[16:31], v[130:133], v[184:187], v[16:31]
	v_exp_f32_e32 v32, v32
	v_exp_f32_e32 v33, v33
	v_exp_f32_e32 v34, v34
	v_exp_f32_e32 v35, v35
	v_mfma_f32_32x32x16_bf16 v[0:15], v[118:121], v[184:187], v[0:15]
	v_exp_f32_e32 v36, v36
	v_exp_f32_e32 v37, v37
	v_exp_f32_e32 v38, v38
	v_exp_f32_e32 v39, v39
	v_mfma_f32_32x32x16_bf16 v[16:31], v[126:129], v[188:191], v[16:31]
	v_exp_f32_e32 v40, v40
	v_exp_f32_e32 v41, v41
	v_exp_f32_e32 v42, v42
	v_exp_f32_e32 v43, v43
	v_mfma_f32_32x32x16_bf16 v[0:15], v[110:113], v[188:191], v[0:15]
	v_exp_f32_e32 v44, v44
	v_exp_f32_e32 v45, v45
	v_exp_f32_e32 v46, v46
	v_exp_f32_e32 v47, v47
	v_add_f32_e32 v150, v48, v49
	v_add_f32_e32 v151, v50, v51
	v_add_f32_e32 v152, v52, v53
	v_add_f32_e32 v153, v54, v55
	v_add_f32_e32 v154, v56, v57
	v_add_f32_e32 v155, v58, v59
	v_add_f32_e32 v156, v60, v61
	v_add_f32_e32 v157, v62, v63
	v_cvt_pk_bf16_f32 v192, v32, v33
	v_cvt_pk_bf16_f32 v193, v34, v35
	v_cvt_pk_bf16_f32 v194, v36, v37
	v_cvt_pk_bf16_f32 v195, v38, v39
	v_cvt_pk_bf16_f32 v196, v40, v41
	v_cvt_pk_bf16_f32 v197, v42, v43
	v_cvt_pk_bf16_f32 v198, v44, v45
	v_cvt_pk_bf16_f32 v199, v46, v47
	v_add_f32_e32 v158, v32, v33
	v_add_f32_e32 v159, v34, v35
	v_mfma_f32_32x32x16_bf16 v[16:31], v[122:125], v[192:195], v[16:31]
	v_add_f32_e32 v160, v36, v37
	v_add_f32_e32 v161, v38, v39
	v_add_f32_e32 v168, v40, v41
	v_add_f32_e32 v169, v42, v43
	v_add_f32_e32 v170, v44, v45
	v_add_f32_e32 v171, v46, v47
	v_mfma_f32_32x32x16_bf16 v[0:15], v[106:109], v[192:195], v[0:15]
	v_add_f32_e32 v150, v150, v158
	v_add_f32_e32 v151, v151, v159
	v_add_f32_e32 v152, v152, v160
	v_add_f32_e32 v153, v153, v161
	v_add_f32_e32 v154, v154, v168
	v_add_f32_e32 v155, v155, v169
	v_mfma_f32_32x32x16_bf16 v[16:31], v[114:117], v[196:199], v[16:31]
	v_add_f32_e32 v156, v156, v170
	v_add_f32_e32 v157, v157, v171
	v_add_f32_e32 v150, v150, v151
	v_add_f32_e32 v152, v152, v153
	v_add_f32_e32 v154, v154, v155
	v_add_f32_e32 v156, v156, v157
	v_mfma_f32_32x32x16_bf16 v[0:15], v[102:105], v[196:199], v[0:15]
	v_add_f32_e32 v150, v150, v152
	v_add_f32_e32 v154, v154, v156
	v_add_f32_e32 v150, v150, v154
	v_add_f32_e32 v135, v135, v150
	s_branch .LBB0_1157
